# early L1 invalidate also in the chip-wide seams 0 and 3
# speedup vs baseline: 1.0433x; 1.0025x over previous
; __device__ __forceinline__ unsigned xb_add(unsigned* p, unsigned v) { return __hip_atomic_fetch_add(p, v, __ATOMIC_RELAXED, __HIP_MEMORY_SCOPE_AGENT); }
; __device__ __forceinline__ void xcd_barrier(const XcdBarrier& b) {
;     asm volatile("s_waitcnt vmcnt(0)" ::: "memory");
;     __syncthreads();
;     if (threadIdx.x == 0) {
;         unsigned* bar = b.bar;
;         __builtin_amdgcn_s_waitcnt(0);
;         unsigned nloc = b.st[0], nx = b.st[1];
;         if (nloc == 0u) { xcd_barrier_complete(bar, b.x, nloc, nx); b.st[0] = nloc; b.st[1] = nx; }
;         const unsigned old = xb_add(&bar[XB_XSUB(b.x)], 1u);
.LBB0_92:
	v_readlane_b32 s72, v251, 22
	v_readlane_b32 s73, v251, 23
	v_writelane_b32 v251, s36, 24
	s_cmp_gt_i32 s85, 1
	s_cselect_b64 s[2:3], -1, 0
	v_writelane_b32 v251, s37, 25
	v_writelane_b32 v251, s38, 26
	v_writelane_b32 v251, s39, 27
	v_writelane_b32 v251, s40, 28
	v_writelane_b32 v251, s41, 29
	v_writelane_b32 v251, s42, 30
	v_writelane_b32 v251, s43, 31
	v_writelane_b32 v251, s44, 32
	v_writelane_b32 v251, s45, 33
	v_writelane_b32 v251, s46, 34
	v_writelane_b32 v251, s47, 35
	v_writelane_b32 v251, s48, 36
	v_writelane_b32 v251, s49, 37
	s_and_b64 s[0:1], s[6:7], s[2:3]
	v_writelane_b32 v251, s50, 38
	s_andn2_b64 vcc, exec, s[0:1]
	v_writelane_b32 v251, s51, 39
	s_cbranch_vccnz .LBB0_146
	s_waitcnt vmcnt(0)
	s_barrier
	s_mov_b64 s[0:1], exec
	v_readlane_b32 s6, v251, 18
	v_readlane_b32 s7, v251, 19
	s_and_b64 s[6:7], s[0:1], s[6:7]
	s_mov_b64 exec, s[6:7]
	s_cbranch_execz .LBB0_145
	buffer_inv sc1
	s_add_i32 s6, 0, 0x20160
	v_mov_b32_e32 v1, s6
	s_waitcnt vmcnt(0) expcnt(0) lgkmcnt(0)
	ds_read_b32 v3, v1
	s_add_i32 s6, 0, 0x20164
	v_mov_b32_e32 v1, s6
	ds_read_b32 v1, v1
	s_waitcnt lgkmcnt(1)
	v_cmp_ne_u32_e32 vcc, 0, v3
	s_cbranch_vccnz .LBB0_109
	v_readlane_b32 s6, v251, 0
	s_mul_i32 s33, s87, s6
	s_add_u32 s6, s66, 0xfd00200
	s_addc_u32 s7, s67, 0
	s_add_u32 s8, s66, 0xfd00400
	s_addc_u32 s9, s67, 0
	s_add_u32 s10, s66, 0xfd00500
	s_addc_u32 s11, s67, 0
	s_add_u32 s12, s66, 0xfd00600
	s_addc_u32 s13, s67, 0
	s_add_u32 s14, s66, 0xfd00700
	s_addc_u32 s15, s67, 0
	s_add_u32 s16, s66, 0xfd00800
	s_addc_u32 s17, s67, 0
	s_add_u32 s18, s66, 0xfd00900
	s_addc_u32 s19, s67, 0
	s_add_u32 s20, s66, 0xfd00a00
	s_addc_u32 s21, s67, 0
	s_add_u32 s22, s66, 0xfd00b00
	s_addc_u32 s23, s67, 0
	s_add_u32 s24, s66, 0xfd00c00
	s_addc_u32 s25, s67, 0
	s_add_u32 s26, s66, 0xfd00d00
	s_addc_u32 s27, s67, 0
	s_add_u32 s28, s66, 0xfd00e00
	s_addc_u32 s29, s67, 0
	s_add_u32 s30, s66, 0xfd00f00
	s_addc_u32 s31, s67, 0
	s_add_u32 s34, s66, 0xfd01000
	s_addc_u32 s35, s67, 0
	s_add_u32 s36, s66, 0xfd01100
	s_addc_u32 s37, s67, 0
	s_add_u32 s38, s66, 0xfd01200
	s_addc_u32 s39, s67, 0
	s_add_u32 s40, s66, 0xfd01300
	s_mul_i32 s33, s33, s86
	s_addc_u32 s41, s67, 0
	s_mov_b32 s48, 1
	v_mov_b32_e32 v17, 0
	s_branch .LBB0_97

; __device__ __forceinline__ unsigned xb_ld(unsigned* p)              { return __hip_atomic_load(p, __ATOMIC_RELAXED, __HIP_MEMORY_SCOPE_AGENT); }
; #define XB_SPIN(cond, bar) do { unsigned _sp = 0; while (cond) { __builtin_amdgcn_s_sleep(1); \
;     if ((++_sp & 255u) == 0u) { if (xb_ld(&(bar)[XB_TMO])) break; if (_sp > XB_SPIN_CAP) { atomicAdd(&(bar)[XB_TMO], 1u); break; } } } } while (0)
; __device__ __forceinline__ void xcd_barrier(const XcdBarrier& b) {
;     ...
;             XB_SPIN(xb_ld(&bar[XB_XGEN(b.x)]) == gen, bar);
;             __builtin_amdgcn_fence(__ATOMIC_ACQUIRE, "agent");
;             asm volatile("s_waitcnt vmcnt(0)" ::: "memory");
.LBB0_124:
	s_or_b64 exec, exec, s[10:11]
	s_waitcnt vmcnt(0)
	s_waitcnt vmcnt(0)

; __device__ __forceinline__ unsigned xb_ld(unsigned* p)              { return __hip_atomic_load(p, __ATOMIC_RELAXED, __HIP_MEMORY_SCOPE_AGENT); }
; __device__ __forceinline__ unsigned xb_add(unsigned* p, unsigned v) { return __hip_atomic_fetch_add(p, v, __ATOMIC_RELAXED, __HIP_MEMORY_SCOPE_AGENT); }
; #define XB_SPIN(cond, bar) do { unsigned _sp = 0; while (cond) { __builtin_amdgcn_s_sleep(1); \
;     if ((++_sp & 255u) == 0u) { if (xb_ld(&(bar)[XB_TMO])) break; if (_sp > XB_SPIN_CAP) { atomicAdd(&(bar)[XB_TMO], 1u); break; } } } } while (0)
; __device__ __forceinline__ void xcd_barrier(const XcdBarrier& b) {
;     ...
;             const unsigned og = xb_add(&bar[XB_TOP], 1u);
;             const unsigned tg = og / nx;
;             if (og + 1u == (tg + 1u) * nx) xb_add(&bar[XB_TOPGEN], 1u);
;             else XB_SPIN(xb_ld(&bar[XB_TOPGEN]) == tg, bar);
;             __builtin_amdgcn_fence(__ATOMIC_ACQUIRE, "agent");
;             xb_add(&bar[XB_XGEN(b.x)], 1u);
.LBB0_142:
	s_or_b64 exec, exec, s[8:9]
	s_mov_b64 s[8:9], exec
	v_mbcnt_lo_u32_b32 v1, s8, 0
	v_mbcnt_hi_u32_b32 v1, s9, v1
	v_cmp_eq_u32_e32 vcc, 0, v1
	s_waitcnt vmcnt(0)
	s_and_saveexec_b64 s[10:11], vcc
	s_cbranch_execz .LBB0_144
	s_bcnt1_i32_b64 s8, s[8:9]
	v_mov_b32_e32 v1, 0x2000
	v_mov_b32_e32 v2, s8
	global_atomic_add v1, v2, s[6:7] offset:1024

; __device__ __forceinline__ unsigned xb_add(unsigned* p, unsigned v) { return __hip_atomic_fetch_add(p, v, __ATOMIC_RELAXED, __HIP_MEMORY_SCOPE_AGENT); }
; __device__ __forceinline__ void xcd_barrier(const XcdBarrier& b) {
;     asm volatile("s_waitcnt vmcnt(0)" ::: "memory");
;     __syncthreads();
;     if (threadIdx.x == 0) {
;         unsigned* bar = b.bar;
;         __builtin_amdgcn_s_waitcnt(0);
;         unsigned nloc = b.st[0], nx = b.st[1];
;         if (nloc == 0u) { xcd_barrier_complete(bar, b.x, nloc, nx); b.st[0] = nloc; b.st[1] = nx; }
;         const unsigned old = xb_add(&bar[XB_XSUB(b.x)], 1u);
.LBB0_604:
	s_cmp_gt_u32 s85, 4
	s_cselect_b64 s[0:1], -1, 0
	v_writelane_b32 v252, s94, 8
	s_and_b64 s[0:1], s[26:27], s[0:1]
	v_readlane_b32 s74, v251, 18
	v_readlane_b32 s68, v251, 20
	v_readlane_b32 s80, v251, 56
	v_writelane_b32 v252, s95, 9
	s_andn2_b64 vcc, exec, s[0:1]
	v_readlane_b32 s75, v251, 19
	v_readlane_b32 s69, v251, 21
	v_readlane_b32 s81, v251, 57
	s_cbranch_vccnz .LBB0_658
	s_waitcnt vmcnt(0)
	s_waitcnt vmcnt(0) lgkmcnt(0)
	s_barrier
	s_and_saveexec_b64 s[0:1], s[74:75]
	s_cbranch_execz .LBB0_657
	buffer_inv sc1
	s_add_i32 s2, 0, 0x20160
	v_mov_b32_e32 v1, s2
	s_waitcnt vmcnt(0) expcnt(0) lgkmcnt(0)
	ds_read_b32 v3, v1
	s_add_i32 s2, 0, 0x20164
	v_mov_b32_e32 v1, s2
	ds_read_b32 v1, v1
	s_waitcnt lgkmcnt(1)
	v_cmp_ne_u32_e32 vcc, 0, v3
	s_cbranch_vccnz .LBB0_621
	v_readlane_b32 s2, v251, 0
	s_mul_i32 s33, s87, s2
	s_add_u32 s2, s66, 0xfd00200
	s_addc_u32 s3, s67, 0
	s_add_u32 s4, s66, 0xfd00400
	s_addc_u32 s5, s67, 0
	s_add_u32 s6, s66, 0xfd00500
	s_addc_u32 s7, s67, 0
	s_add_u32 s8, s66, 0xfd00600
	s_addc_u32 s9, s67, 0
	s_add_u32 s10, s66, 0xfd00700
	s_addc_u32 s11, s67, 0
	s_add_u32 s12, s66, 0xfd00800
	s_addc_u32 s13, s67, 0
	s_add_u32 s14, s66, 0xfd00900
	s_addc_u32 s15, s67, 0
	s_add_u32 s16, s66, 0xfd00a00
	s_addc_u32 s17, s67, 0
	s_add_u32 s18, s66, 0xfd00b00
	s_addc_u32 s19, s67, 0
	s_add_u32 s20, s66, 0xfd00c00
	s_addc_u32 s21, s67, 0
	s_add_u32 s22, s66, 0xfd00d00
	s_addc_u32 s23, s67, 0
	s_add_u32 s24, s66, 0xfd00e00
	s_addc_u32 s25, s67, 0
	s_add_u32 s26, s66, 0xfd00f00
	s_addc_u32 s27, s67, 0
	s_add_u32 s28, s66, 0xfd01000
	s_addc_u32 s29, s67, 0
	s_add_u32 s30, s66, 0xfd01100
	s_addc_u32 s31, s67, 0
	s_add_u32 s34, s66, 0xfd01200
	s_addc_u32 s35, s67, 0
	s_add_u32 s36, s66, 0xfd01300
	s_mul_i32 s33, s33, s86
	s_addc_u32 s37, s67, 0
	s_mov_b32 s44, 1
	v_mov_b32_e32 v17, 0
	s_branch .LBB0_609

; __device__ __forceinline__ unsigned xb_ld(unsigned* p)              { return __hip_atomic_load(p, __ATOMIC_RELAXED, __HIP_MEMORY_SCOPE_AGENT); }
; #define XB_SPIN(cond, bar) do { unsigned _sp = 0; while (cond) { __builtin_amdgcn_s_sleep(1); \
;     if ((++_sp & 255u) == 0u) { if (xb_ld(&(bar)[XB_TMO])) break; if (_sp > XB_SPIN_CAP) { atomicAdd(&(bar)[XB_TMO], 1u); break; } } } } while (0)
; __device__ __forceinline__ void xcd_barrier(const XcdBarrier& b) {
;     ...
;             XB_SPIN(xb_ld(&bar[XB_XGEN(b.x)]) == gen, bar);
;             __builtin_amdgcn_fence(__ATOMIC_ACQUIRE, "agent");
;             asm volatile("s_waitcnt vmcnt(0)" ::: "memory");
.LBB0_636:
	s_or_b64 exec, exec, s[6:7]
	s_waitcnt vmcnt(0)
	s_waitcnt vmcnt(0)

; __device__ __forceinline__ unsigned xb_ld(unsigned* p)              { return __hip_atomic_load(p, __ATOMIC_RELAXED, __HIP_MEMORY_SCOPE_AGENT); }
; __device__ __forceinline__ unsigned xb_add(unsigned* p, unsigned v) { return __hip_atomic_fetch_add(p, v, __ATOMIC_RELAXED, __HIP_MEMORY_SCOPE_AGENT); }
; #define XB_SPIN(cond, bar) do { unsigned _sp = 0; while (cond) { __builtin_amdgcn_s_sleep(1); \
;     if ((++_sp & 255u) == 0u) { if (xb_ld(&(bar)[XB_TMO])) break; if (_sp > XB_SPIN_CAP) { atomicAdd(&(bar)[XB_TMO], 1u); break; } } } } while (0)
; __device__ __forceinline__ void xcd_barrier(const XcdBarrier& b) {
;     ...
;             const unsigned og = xb_add(&bar[XB_TOP], 1u);
;             const unsigned tg = og / nx;
;             if (og + 1u == (tg + 1u) * nx) xb_add(&bar[XB_TOPGEN], 1u);
;             else XB_SPIN(xb_ld(&bar[XB_TOPGEN]) == tg, bar);
;             __builtin_amdgcn_fence(__ATOMIC_ACQUIRE, "agent");
;             xb_add(&bar[XB_XGEN(b.x)], 1u);
.LBB0_654:
	s_or_b64 exec, exec, s[4:5]
	s_mov_b64 s[4:5], exec
	v_mbcnt_lo_u32_b32 v1, s4, 0
	v_mbcnt_hi_u32_b32 v1, s5, v1
	v_cmp_eq_u32_e32 vcc, 0, v1
	s_waitcnt vmcnt(0)
	s_and_saveexec_b64 s[6:7], vcc
	s_cbranch_execz .LBB0_656
	s_bcnt1_i32_b64 s4, s[4:5]
	v_mov_b32_e32 v1, 0x2000
	v_mov_b32_e32 v2, s4
	global_atomic_add v1, v2, s[2:3] offset:1024
